# diff-attn QK segments: no exps ahead of the first MFMA, all 16 spread into the MFMA gaps
# baseline (speedup 1.0000x reference)
; __device__ __forceinline__ void finishSM(f32x16& p0, f32x16& p1, float alpha, float& l_reg, bf16x8& pa0, bf16x8& pa1, bf16x8& pa2, bf16x8& pa3) {
;     for (int r = 0; r < 16; ++r) p1[r] = __builtin_amdgcn_exp2f(p1[r]);
;     float ps = 0; for (int r = 0; r < 16; ++r) ps += p0[r]; for (int r = 0; r < 16; ++r) ps += p1[r];
;     { auto rr = __builtin_amdgcn_permlane32_swap(__float_as_uint(ps), __float_as_uint(ps), false, false);
;       ps = __uint_as_float(rr[0]) + __uint_as_float(rr[1]); }
;     l_reg = l_reg * alpha + ps;
;     ...
;     PK4(p0, 0, pa0); PK4(p0, 8, pa1); PK4(p1, 0, pa2); PK4(p1, 8, pa3);
;     ...
; }
; template <int KB, bool SK>
; __device__ __forceinline__ void qkt(f32x16& p0, f32x16& p1, const char* K_lds, int r32, int hi, const bf16x8* qr, bool act) {
;     if (SK && !act) { const float NEG = -__builtin_inff();
; #pragma unroll
;         for (int r = 0; r < 16; ++r) { p0[r] = NEG; p1[r] = NEG; } return; }
;     p0 = f32x16{}; p1 = f32x16{};
;     const char* kb[4];
; #pragma unroll
;     for (int dd = 0; dd < 4; ++dd) kb[dd] = K_lds + KB * SHM_K + KSWZ(r32, (dd * 16 + hi * 8) * 2);
; #pragma unroll
;     for (int d0 = 0; d0 < 8; ++d0) { const char* a = kb[d0 & 3] + (d0 >> 2) * 128;
;         bf16x8 b0 = *reinterpret_cast<const bf16x8*>(a);
;         bf16x8 b1 = *reinterpret_cast<const bf16x8*>(a + 32 * 256);
;         const bf16x8 qf = qr[d0];
;         p0 = __builtin_amdgcn_mfma_f32_32x32x16_bf16(b0, qf, p0, 0, 0, 0);
;         p1 = __builtin_amdgcn_mfma_f32_32x32x16_bf16(b1, qf, p1, 0, 0, 0); }
; }
.Lattn_prio_skip:
.LBB0_1129:
	ds_read_b128 v[180:183], v211 offset:49152
	ds_read_b128 v[184:187], v211 offset:57344
	ds_read_b128 v[188:191], v212 offset:49152
	ds_read_b128 v[228:231], v212 offset:57344
	ds_read_b128 v[232:235], v213 offset:49152
	ds_read_b128 v[236:239], v213 offset:57344
	ds_read_b128 v[240:243], v214 offset:49152
	ds_read_b128 v[244:247], v214 offset:57344
	s_add_i32 s4, s26, 0xffffff81
	s_sub_i32 s5, s26, 64
	s_waitcnt lgkmcnt(7)
	v_mfma_f32_32x32x16_bf16 v[86:101], v[180:183], v[158:161], 0
	ds_read_b128 v[180:183], v211 offset:49280
	v_exp_f32_e32 v126, v126
	v_exp_f32_e32 v127, v127
	v_exp_f32_e32 v124, v124
	v_exp_f32_e32 v125, v125
	v_exp_f32_e32 v120, v120
	s_waitcnt lgkmcnt(7)
	v_mfma_f32_32x32x16_bf16 v[70:85], v[184:187], v[158:161], 0
	ds_read_b128 v[184:187], v211 offset:57472
	v_exp_f32_e32 v121, v121
	v_exp_f32_e32 v116, v116
	v_exp_f32_e32 v117, v117
	v_exp_f32_e32 v114, v114
	v_exp_f32_e32 v115, v115
	s_waitcnt lgkmcnt(7)
	v_mfma_f32_32x32x16_bf16 v[86:101], v[188:191], v[154:157], v[86:101]
	ds_read_b128 v[188:191], v212 offset:49280
	v_exp_f32_e32 v128, v128
	v_exp_f32_e32 v129, v129
	v_exp_f32_e32 v122, v122
	v_exp_f32_e32 v123, v123
	v_exp_f32_e32 v118, v118
	s_waitcnt lgkmcnt(7)
	v_mfma_f32_32x32x16_bf16 v[70:85], v[228:231], v[154:157], v[70:85]
	ds_read_b128 v[228:231], v212 offset:57472
	v_exp_f32_e32 v119, v119
	v_add_f32_e32 v179, 0, v170
	v_add_f32_e32 v179, v171, v179
	v_add_f32_e32 v179, v172, v179
	v_add_f32_e32 v179, v173, v179
	s_waitcnt lgkmcnt(7)
	v_mfma_f32_32x32x16_bf16 v[86:101], v[232:235], v[150:153], v[86:101]
	ds_read_b128 v[232:235], v213 offset:49280
	v_add_f32_e32 v179, v174, v179
	v_add_f32_e32 v179, v176, v179
	v_add_f32_e32 v179, v175, v179
	v_add_f32_e32 v179, v177, v179
	v_add_f32_e32 v179, v162, v179
	s_waitcnt lgkmcnt(7)
	v_mfma_f32_32x32x16_bf16 v[70:85], v[236:239], v[150:153], v[70:85]
	ds_read_b128 v[236:239], v213 offset:57472
	v_add_f32_e32 v179, v163, v179
	v_add_f32_e32 v110, v164, v179
	v_add_f32_e32 v110, v166, v110
	v_add_f32_e32 v110, v165, v110
	v_add_f32_e32 v110, v167, v110
	s_waitcnt lgkmcnt(7)
	v_mfma_f32_32x32x16_bf16 v[86:101], v[240:243], v[134:137], v[86:101]
	ds_read_b128 v[240:243], v214 offset:49280
	v_add_f32_e32 v110, v168, v110
	v_add_f32_e32 v110, v169, v110
	v_add_f32_e32 v110, v126, v110
	v_add_f32_e32 v102, v127, v110
	v_add_f32_e32 v102, v124, v102
	s_waitcnt lgkmcnt(7)
	v_mfma_f32_32x32x16_bf16 v[70:85], v[244:247], v[134:137], v[70:85]
	ds_read_b128 v[244:247], v214 offset:57472
	v_add_f32_e32 v102, v125, v102
	v_add_f32_e32 v102, v120, v102
	v_add_f32_e32 v102, v121, v102
	v_add_f32_e32 v102, v116, v102
	v_add_f32_e32 v102, v117, v102
	s_waitcnt lgkmcnt(7)
	v_mfma_f32_32x32x16_bf16 v[86:101], v[180:183], v[138:141], v[86:101]
	v_add_f32_e32 v102, v114, v102
	v_add_f32_e32 v102, v115, v102
	v_add_f32_e32 v102, v128, v102
	v_add_f32_e32 v102, v129, v102
	v_add_f32_e32 v102, v122, v102
	s_waitcnt lgkmcnt(6)
	v_mfma_f32_32x32x16_bf16 v[70:85], v[184:187], v[138:141], v[70:85]
	v_add_f32_e32 v102, v123, v102
	v_add_f32_e32 v102, v118, v102
	v_add_f32_e32 v223, v119, v102
	v_mov_b32_e32 v224, v223
	s_nop 1
	v_permlane32_swap_b32_e32 v223, v224
	s_waitcnt lgkmcnt(5)
	v_mfma_f32_32x32x16_bf16 v[86:101], v[188:191], v[142:145], v[86:101]
	v_cvt_pk_bf16_f32 v102, v170, v171
	v_cvt_pk_bf16_f32 v103, v172, v173
	v_cvt_pk_bf16_f32 v104, v174, v176
	v_cvt_pk_bf16_f32 v105, v175, v177
	s_waitcnt lgkmcnt(4)
	v_mfma_f32_32x32x16_bf16 v[70:85], v[228:231], v[142:145], v[70:85]
	v_cvt_pk_bf16_f32 v66, v162, v163
	v_cvt_pk_bf16_f32 v67, v164, v166
	v_cvt_pk_bf16_f32 v68, v165, v167
	v_cvt_pk_bf16_f32 v69, v168, v169
	s_waitcnt lgkmcnt(3)
	v_mfma_f32_32x32x16_bf16 v[86:101], v[232:235], v[146:149], v[86:101]
	v_cvt_pk_bf16_f32 v106, v126, v127
	v_cvt_pk_bf16_f32 v107, v124, v125
	v_cvt_pk_bf16_f32 v108, v120, v121
	v_cvt_pk_bf16_f32 v109, v116, v117
	s_waitcnt lgkmcnt(2)
	v_mfma_f32_32x32x16_bf16 v[70:85], v[236:239], v[146:149], v[70:85]
	v_cvt_pk_bf16_f32 v110, v114, v115
	v_cvt_pk_bf16_f32 v111, v128, v129
	v_cvt_pk_bf16_f32 v112, v122, v123
	v_cvt_pk_bf16_f32 v113, v118, v119
	s_waitcnt lgkmcnt(1)
	v_mfma_f32_32x32x16_bf16 v[86:101], v[240:243], v[130:133], v[86:101]
	s_nop 1
	v_permlane32_swap_b32_e32 v102, v104
	v_permlane32_swap_b32_e32 v103, v105
	v_permlane32_swap_b32_e32 v66, v68
	v_permlane32_swap_b32_e32 v67, v69
	s_waitcnt lgkmcnt(0)
	v_mfma_f32_32x32x16_bf16 v[70:85], v[244:247], v[130:133], v[70:85]
	v_permlane32_swap_b32_e32 v106, v108
	v_permlane32_swap_b32_e32 v107, v109
	v_permlane32_swap_b32_e32 v110, v112
	v_permlane32_swap_b32_e32 v111, v113
	v_add_u32_e32 v114, 0x2000, v255
	global_load_dwordx4 v[162:165], v255, s[42:43]
	global_load_dwordx4 v[166:169], v114, s[42:43]
	global_load_dwordx4 v[170:173], v255, s[22:23]
	global_load_dwordx4 v[174:177], v114, s[22:23]
	s_cmp_le_i32 s5, s13
	s_cselect_b64 s[52:53], -1, 0
	s_cmp_gt_i32 s4, s15
	s_cselect_b64 s[4:5], -1, 0
	s_and_b64 s[4:5], s[52:53], s[4:5]
	s_and_b64 vcc, exec, s[4:5]
	ds_read_b64_tr_b16 v[114:115], v202 offset:0x0
	ds_read_b64_tr_b16 v[116:117], v202 offset:0x800
	ds_read_b64_tr_b16 v[118:119], v202 offset:0x1000
	ds_read_b64_tr_b16 v[120:121], v202 offset:0x1800
	ds_read_b64_tr_b16 v[122:123], v202 offset:0x2000
	ds_read_b64_tr_b16 v[124:125], v202 offset:0x2800
	ds_read_b64_tr_b16 v[126:127], v202 offset:0x3000
	ds_read_b64_tr_b16 v[128:129], v202 offset:0x3800
	ds_read_b64_tr_b16 v[182:183], v202 offset:0x200
	ds_read_b64_tr_b16 v[184:185], v202 offset:0xa00
	ds_read_b64_tr_b16 v[186:187], v202 offset:0x1200
	ds_read_b64_tr_b16 v[188:189], v202 offset:0x1a00
	ds_read_b64_tr_b16 v[190:191], v202 offset:0x2200
	ds_read_b64_tr_b16 v[192:193], v202 offset:0x2a00
	s_cbranch_vccnz .Lh1_nomask
; __device__ __forceinline__ void mask_tile(f32x16& p0, f32x16& p1, int dq, unsigned W) {
;     const float NEG = -__builtin_inff();
; #pragma unroll
;     for (int r = 0; r < 16; ++r) {
;         const int c = (r & 3) + 8 * (r >> 2);
;         if ((unsigned)(dq - c) >= W) p0[r] = NEG;
;         if ((unsigned)(dq - c - 32) >= W) p1[r] = NEG;
;     }
; }
	v_add_u32_e32 v226, s80, v222
	v_subrev_u32_e32 v240, 64, v226
	v_cmp_gt_u32_e32 vcc, s85, v240
	v_add_u32_e32 v240, 0xffffffa0, v226
	s_nop 0
	v_cndmask_b32_e32 v86, v215, v86, vcc
	v_cmp_gt_u32_e32 vcc, s85, v240
	v_add_u32_e32 v240, 0xffffffbf, v226
	s_nop 0
	v_cndmask_b32_e32 v70, v215, v70, vcc
	v_cmp_gt_u32_e32 vcc, s85, v240
	v_add_u32_e32 v240, 0xffffff9f, v226
	s_nop 0
	v_cndmask_b32_e32 v87, v215, v87, vcc
	v_cmp_gt_u32_e32 vcc, s85, v240
	v_add_u32_e32 v240, 0xffffffbe, v226
	s_nop 0
	v_cndmask_b32_e32 v71, v215, v71, vcc
	v_cmp_gt_u32_e32 vcc, s85, v240
	v_add_u32_e32 v240, 0xffffff9e, v226
	s_nop 0
	v_cndmask_b32_e32 v88, v215, v88, vcc
	v_cmp_gt_u32_e32 vcc, s85, v240
	v_add_u32_e32 v240, 0xffffffbd, v226
	s_nop 0
	v_cndmask_b32_e32 v72, v215, v72, vcc
	v_cmp_gt_u32_e32 vcc, s85, v240
	v_add_u32_e32 v240, 0xffffff9d, v226
	s_nop 0
	v_cndmask_b32_e32 v89, v215, v89, vcc
	v_cmp_gt_u32_e32 vcc, s85, v240
	v_add_u32_e32 v240, 0xffffffb8, v226
	s_nop 0
	v_cndmask_b32_e32 v73, v215, v73, vcc
	v_cmp_gt_u32_e32 vcc, s85, v240
	v_add_u32_e32 v240, 0xffffff98, v226
	s_nop 0
	v_cndmask_b32_e32 v90, v215, v90, vcc
	v_cmp_gt_u32_e32 vcc, s85, v240
	v_add_u32_e32 v240, 0xffffffb7, v226
	s_nop 0
	v_cndmask_b32_e32 v74, v215, v74, vcc
	v_cmp_gt_u32_e32 vcc, s85, v240
	v_add_u32_e32 v240, 0xffffff97, v226
	s_nop 0
	v_cndmask_b32_e32 v91, v215, v91, vcc
	v_cmp_gt_u32_e32 vcc, s85, v240
	v_add_u32_e32 v240, 0xffffffb6, v226
	s_nop 0
	v_cndmask_b32_e32 v75, v215, v75, vcc
	v_cmp_gt_u32_e32 vcc, s85, v240
	v_add_u32_e32 v240, 0xffffff96, v226
	s_nop 0
	v_cndmask_b32_e32 v92, v215, v92, vcc
	v_cmp_gt_u32_e32 vcc, s85, v240
	v_add_u32_e32 v240, 0xffffffb5, v226
	s_nop 0
	v_cndmask_b32_e32 v76, v215, v76, vcc
	v_cmp_gt_u32_e32 vcc, s85, v240
	v_add_u32_e32 v240, 0xffffff95, v226
	s_nop 0
	v_cndmask_b32_e32 v93, v215, v93, vcc
	v_cmp_gt_u32_e32 vcc, s85, v240
	v_add_u32_e32 v240, 0xffffffb0, v226
	s_nop 0
	v_cndmask_b32_e32 v77, v215, v77, vcc
	v_cmp_gt_u32_e32 vcc, s85, v240
	v_add_u32_e32 v240, 0xffffff90, v226
	s_nop 0
	v_cndmask_b32_e32 v94, v215, v94, vcc
	v_cmp_gt_u32_e32 vcc, s85, v240
	v_add_u32_e32 v240, 0xffffffaf, v226
	s_nop 0
	v_cndmask_b32_e32 v78, v215, v78, vcc
	v_cmp_gt_u32_e32 vcc, s85, v240
	v_add_u32_e32 v240, 0xffffff8f, v226
	s_nop 0
	v_cndmask_b32_e32 v95, v215, v95, vcc
	v_cmp_gt_u32_e32 vcc, s85, v240
	v_add_u32_e32 v240, 0xffffffae, v226
	s_nop 0
	v_cndmask_b32_e32 v79, v215, v79, vcc
	v_cmp_gt_u32_e32 vcc, s85, v240
	v_add_u32_e32 v240, 0xffffff8e, v226
	s_nop 0
	v_cndmask_b32_e32 v96, v215, v96, vcc
	v_cmp_gt_u32_e32 vcc, s85, v240
	v_add_u32_e32 v240, 0xffffffad, v226
	s_nop 0
	v_cndmask_b32_e32 v80, v215, v80, vcc
	v_cmp_gt_u32_e32 vcc, s85, v240
	v_add_u32_e32 v240, 0xffffff8d, v226
	s_nop 0
	v_cndmask_b32_e32 v97, v215, v97, vcc
	v_cmp_gt_u32_e32 vcc, s85, v240
	v_add_u32_e32 v240, 0xffffffa8, v226
	s_nop 0
	v_cndmask_b32_e32 v81, v215, v81, vcc
	v_cmp_gt_u32_e32 vcc, s85, v240
	v_add_u32_e32 v240, 0xffffff88, v226
	s_nop 0
	v_cndmask_b32_e32 v98, v215, v98, vcc
	v_cmp_gt_u32_e32 vcc, s85, v240
	v_add_u32_e32 v240, 0xffffffa7, v226
	s_nop 0
	v_cndmask_b32_e32 v82, v215, v82, vcc
	v_cmp_gt_u32_e32 vcc, s85, v240
	v_add_u32_e32 v240, 0xffffff87, v226
	s_nop 0
	v_cndmask_b32_e32 v99, v215, v99, vcc
	v_cmp_gt_u32_e32 vcc, s85, v240
	v_add_u32_e32 v240, 0xffffffa6, v226
	s_nop 0
	v_cndmask_b32_e32 v83, v215, v83, vcc
	v_cmp_gt_u32_e32 vcc, s85, v240
	v_add_u32_e32 v240, 0xffffff86, v226
	s_nop 0
	v_cndmask_b32_e32 v100, v215, v100, vcc
	v_cmp_gt_u32_e32 vcc, s85, v240
	v_add_u32_e32 v240, 0xffffffa5, v226
	s_nop 0
	v_cndmask_b32_e32 v84, v215, v84, vcc
	v_cmp_gt_u32_e32 vcc, s85, v240
	v_add_u32_e32 v240, 0xffffff85, v226
	s_nop 0
	v_cndmask_b32_e32 v101, v215, v101, vcc
	v_cmp_gt_u32_e32 vcc, s85, v240
	s_nop 1
	v_cndmask_b32_e32 v85, v215, v85, vcc

; __device__ __forceinline__ void finishSM(f32x16& p0, f32x16& p1, float alpha, float& l_reg, bf16x8& pa0, bf16x8& pa1, bf16x8& pa2, bf16x8& pa3) {
;     for (int r = 0; r < 16; ++r) p1[r] = __builtin_amdgcn_exp2f(p1[r]);
;     float ps = 0; for (int r = 0; r < 16; ++r) ps += p0[r]; for (int r = 0; r < 16; ++r) ps += p1[r];
;     { auto rr = __builtin_amdgcn_permlane32_swap(__float_as_uint(ps), __float_as_uint(ps), false, false);
;       ps = __uint_as_float(rr[0]) + __uint_as_float(rr[1]); }
;     l_reg = l_reg * alpha + ps;
;     ...
;     PK4(p0, 0, pa0); PK4(p0, 8, pa1); PK4(p1, 0, pa2); PK4(p1, 8, pa3);
;     ...
; }
; template <int KB, bool SK>
; __device__ __forceinline__ void qkt(f32x16& p0, f32x16& p1, const char* K_lds, int r32, int hi, const bf16x8* qr, bool act) {
;     if (SK && !act) { const float NEG = -__builtin_inff();
; #pragma unroll
;         for (int r = 0; r < 16; ++r) { p0[r] = NEG; p1[r] = NEG; } return; }
;     p0 = f32x16{}; p1 = f32x16{};
;     const char* kb[4];
; #pragma unroll
;     for (int dd = 0; dd < 4; ++dd) kb[dd] = K_lds + KB * SHM_K + KSWZ(r32, (dd * 16 + hi * 8) * 2);
; #pragma unroll
;     for (int d0 = 0; d0 < 8; ++d0) { const char* a = kb[d0 & 3] + (d0 >> 2) * 128;
;         bf16x8 b0 = *reinterpret_cast<const bf16x8*>(a);
;         bf16x8 b1 = *reinterpret_cast<const bf16x8*>(a + 32 * 256);
;         const bf16x8 qf = qr[d0];
;         p0 = __builtin_amdgcn_mfma_f32_32x32x16_bf16(b0, qf, p0, 0, 0, 0);
;         p1 = __builtin_amdgcn_mfma_f32_32x32x16_bf16(b1, qf, p1, 0, 0, 0); }
; }
.Lh1_noresc:
	v_exp_f32_e32 v66, v228
	v_exp_f32_e32 v67, v229
	v_exp_f32_e32 v68, v230
	v_exp_f32_e32 v69, v231
	v_exp_f32_e32 v70, v232
	v_exp_f32_e32 v71, v233
	v_exp_f32_e32 v72, v234
	v_exp_f32_e32 v73, v235
	v_exp_f32_e32 v74, v236
	v_exp_f32_e32 v75, v237
	v_exp_f32_e32 v76, v238
	v_exp_f32_e32 v77, v239
	v_exp_f32_e32 v78, v98
	v_exp_f32_e32 v79, v99
	v_exp_f32_e32 v80, v100
	v_exp_f32_e32 v81, v101
	s_waitcnt lgkmcnt(0)
	s_barrier
	ds_read_b128 v[162:165], v211 offset:32768
	ds_read_b128 v[166:169], v211 offset:40960
	ds_read_b128 v[170:173], v212 offset:32768
	ds_read_b128 v[174:177], v212 offset:40960
	ds_read_b128 v[230:233], v213 offset:32768
	ds_read_b128 v[234:237], v213 offset:40960
	ds_read_b128 v[238:241], v214 offset:32768
	ds_read_b128 v[242:245], v214 offset:40960
	s_waitcnt lgkmcnt(7)
	v_mfma_f32_32x32x16_bf16 v[114:129], v[162:165], v[158:161], 0
	ds_read_b128 v[162:165], v211 offset:32896
	v_exp_f32_e32 v82, v86
	v_exp_f32_e32 v83, v95
	v_exp_f32_e32 v84, v96
	v_exp_f32_e32 v85, v97
	v_exp_f32_e32 v86, v179
	s_waitcnt lgkmcnt(7)
	v_mfma_f32_32x32x16_bf16 v[98:113], v[166:169], v[158:161], 0
	ds_read_b128 v[166:169], v211 offset:41088
	v_exp_f32_e32 v87, v87
	v_exp_f32_e32 v88, v88
	v_exp_f32_e32 v89, v89
	v_exp_f32_e32 v90, v90
	v_exp_f32_e32 v91, v91
	s_waitcnt lgkmcnt(7)
	v_mfma_f32_32x32x16_bf16 v[114:129], v[170:173], v[154:157], v[114:129]
	ds_read_b128 v[170:173], v212 offset:32896
	v_exp_f32_e32 v92, v92
	v_exp_f32_e32 v93, v93
	v_exp_f32_e32 v94, v94
	v_exp_f32_e32 v95, v180
	v_exp_f32_e32 v96, v181
	s_waitcnt lgkmcnt(7)
	v_mfma_f32_32x32x16_bf16 v[98:113], v[174:177], v[154:157], v[98:113]
	ds_read_b128 v[174:177], v212 offset:41088
	v_exp_f32_e32 v97, v178
	v_add_f32_e32 v178, 0, v66
	v_add_f32_e32 v178, v67, v178
	v_add_f32_e32 v178, v68, v178
	v_add_f32_e32 v178, v69, v178
	s_waitcnt lgkmcnt(7)
	v_mfma_f32_32x32x16_bf16 v[114:129], v[230:233], v[150:153], v[114:129]
	ds_read_b128 v[230:233], v213 offset:32896
	v_add_f32_e32 v178, v70, v178
	v_add_f32_e32 v178, v71, v178
	v_add_f32_e32 v178, v72, v178
	v_add_f32_e32 v178, v73, v178
	v_add_f32_e32 v178, v74, v178
	s_waitcnt lgkmcnt(7)
	v_mfma_f32_32x32x16_bf16 v[98:113], v[234:237], v[150:153], v[98:113]
	ds_read_b128 v[234:237], v213 offset:41088
	v_add_f32_e32 v178, v75, v178
	v_add_f32_e32 v178, v76, v178
	v_add_f32_e32 v178, v77, v178
	v_add_f32_e32 v178, v78, v178
	v_add_f32_e32 v178, v79, v178
	s_waitcnt lgkmcnt(7)
	v_mfma_f32_32x32x16_bf16 v[114:129], v[238:241], v[134:137], v[114:129]
	ds_read_b128 v[238:241], v214 offset:32896
	v_add_f32_e32 v178, v80, v178
	v_add_f32_e32 v178, v81, v178
	v_add_f32_e32 v178, v82, v178
	v_add_f32_e32 v178, v83, v178
	v_add_f32_e32 v178, v84, v178
	s_waitcnt lgkmcnt(7)
	v_mfma_f32_32x32x16_bf16 v[98:113], v[242:245], v[134:137], v[98:113]
	ds_read_b128 v[242:245], v214 offset:41088
	v_add_f32_e32 v178, v85, v178
	v_add_f32_e32 v178, v86, v178
	v_add_f32_e32 v178, v87, v178
	v_add_f32_e32 v178, v88, v178
	v_add_f32_e32 v178, v89, v178
	s_waitcnt lgkmcnt(7)
	v_mfma_f32_32x32x16_bf16 v[114:129], v[162:165], v[138:141], v[114:129]
	v_add_f32_e32 v178, v90, v178
	v_add_f32_e32 v178, v91, v178
	v_add_f32_e32 v178, v92, v178
	v_add_f32_e32 v178, v93, v178
	v_add_f32_e32 v178, v94, v178
	s_waitcnt lgkmcnt(6)
	v_mfma_f32_32x32x16_bf16 v[98:113], v[166:169], v[138:141], v[98:113]
	v_add_f32_e32 v178, v95, v178
	v_add_f32_e32 v178, v96, v178
	v_add_f32_e32 v228, v97, v178
	v_mov_b32_e32 v229, v228
	s_nop 1
	v_permlane32_swap_b32_e32 v228, v229
	s_waitcnt lgkmcnt(5)
	v_mfma_f32_32x32x16_bf16 v[114:129], v[170:173], v[142:145], v[114:129]
	v_cvt_pk_bf16_f32 v178, v66, v67
	v_cvt_pk_bf16_f32 v179, v68, v69
	v_cvt_pk_bf16_f32 v180, v70, v71
	v_cvt_pk_bf16_f32 v181, v72, v73
	s_waitcnt lgkmcnt(4)
	v_mfma_f32_32x32x16_bf16 v[98:113], v[174:177], v[142:145], v[98:113]
	v_cvt_pk_bf16_f32 v182, v74, v75
	v_cvt_pk_bf16_f32 v183, v76, v77
	v_cvt_pk_bf16_f32 v184, v78, v79
	v_cvt_pk_bf16_f32 v185, v80, v81
	s_waitcnt lgkmcnt(3)
	v_mfma_f32_32x32x16_bf16 v[114:129], v[230:233], v[146:149], v[114:129]
	v_cvt_pk_bf16_f32 v186, v82, v83
	v_cvt_pk_bf16_f32 v187, v84, v85
	v_cvt_pk_bf16_f32 v188, v86, v87
	v_cvt_pk_bf16_f32 v189, v88, v89
	s_waitcnt lgkmcnt(2)
	v_mfma_f32_32x32x16_bf16 v[98:113], v[234:237], v[146:149], v[98:113]
	v_cvt_pk_bf16_f32 v190, v90, v91
	v_cvt_pk_bf16_f32 v191, v92, v93
	v_cvt_pk_bf16_f32 v192, v94, v95
	v_cvt_pk_bf16_f32 v193, v96, v97
	s_waitcnt lgkmcnt(1)
	v_mfma_f32_32x32x16_bf16 v[114:129], v[238:241], v[130:133], v[114:129]
	s_nop 1
	v_permlane32_swap_b32_e32 v178, v180
	v_permlane32_swap_b32_e32 v179, v181
	v_permlane32_swap_b32_e32 v182, v184
	v_permlane32_swap_b32_e32 v183, v185
	s_waitcnt lgkmcnt(0)
	v_mfma_f32_32x32x16_bf16 v[98:113], v[242:245], v[130:133], v[98:113]
	v_permlane32_swap_b32_e32 v186, v188
	v_permlane32_swap_b32_e32 v187, v189
	v_permlane32_swap_b32_e32 v190, v192
	v_permlane32_swap_b32_e32 v191, v193
	s_add_i32 s4, s25, 1
	s_cmp_le_u32 s4, s24
	s_cselect_b64 s[76:77], -1, 0
	s_cmp_gt_u32 s4, s24
	s_cbranch_scc1 .LBB0_1137
	v_add_u32_e32 v84, 0x4000, v255
	v_add_u32_e32 v85, 0x6000, v255
	global_load_dwordx4 v[162:165], v84, s[42:43]
	global_load_dwordx4 v[166:169], v85, s[42:43]
	global_load_dwordx4 v[170:173], v84, s[22:23]
	global_load_dwordx4 v[174:177], v85, s[22:23]
